# attention QK: batch the 8 K-fragment ds_read_b128 up front with counted lgkmcnt waits (14 blocks)
# speedup vs baseline: 1.0357x; 1.0037x over previous
; #define LAS __attribute__((address_space(3)))
; template <bool HAS_POST, class MaskF>
; __device__ __forceinline__ void attn_run(LAS unsigned char* lds, const bf16* Kg, const bf16* Vg, int pitch, int t0, int t1,
;                                          const bf16x8 (&qr)[4], f32x16& o0, f32x16& o1, f32x16& o2, MaskF& mf, const int wv) {
;     ...
;             LAS unsigned char* Kb = lds + (cur * 2 + j) * KBUF + cx.kroff;
;             if (wv < 4) __builtin_amdgcn_s_setprio(1);
; #pragma unroll
;             for (int d0 = 0; d0 < 4; ++d0) {
;                 const bf16x8 a0 = *(const LAS bf16x8*)(Kb + d0 * 32), a1 = *(const LAS bf16x8*)(Kb + 32 * 144 + d0 * 32);
;                 if (d0 == 0) { p0 = __builtin_amdgcn_mfma_f32_32x32x16_bf16(a0, qr[0], zc, 0, 0, 0); p1 = __builtin_amdgcn_mfma_f32_32x32x16_bf16(a1, qr[0], zc, 0, 0, 0); }
;                 else { p0 = __builtin_amdgcn_mfma_f32_32x32x16_bf16(a0, qr[d0], p0, 0, 0, 0); p1 = __builtin_amdgcn_mfma_f32_32x32x16_bf16(a1, qr[d0], p1, 0, 0, 0); }
;             }
.LBB0_858:
	s_mul_i32 s0, s18, 0x2400
	v_add_u32_e32 v106, s0, v167
	ds_read_b128 v[102:105], v106
	ds_read_b128 v[110:113], v106 offset:32
	ds_read_b128 v[50:53], v106 offset:4608
	ds_read_b128 v[132:135], v106 offset:4640
	ds_read_b128 v[136:139], v106 offset:64
	ds_read_b128 v[140:143], v106 offset:4672
	ds_read_b128 v[144:147], v106 offset:96
	ds_read_b128 v[148:151], v106 offset:4704
	s_and_b64 vcc, exec, s[8:9]
	s_waitcnt lgkmcnt(7)
	v_mfma_f32_32x32x16_bf16 v[66:81], v[102:105], v[116:119], 0
	s_waitcnt lgkmcnt(6)
	v_mfma_f32_32x32x16_bf16 v[66:81], v[110:113], v[120:123], v[66:81]
	s_waitcnt lgkmcnt(5)
	v_mfma_f32_32x32x16_bf16 v[50:65], v[50:53], v[116:119], 0
	s_waitcnt lgkmcnt(4)
	v_mfma_f32_32x32x16_bf16 v[50:65], v[132:135], v[120:123], v[50:65]
	s_waitcnt lgkmcnt(3)
	v_mfma_f32_32x32x16_bf16 v[66:81], v[136:139], v[124:127], v[66:81]
	s_waitcnt lgkmcnt(2)
	v_mfma_f32_32x32x16_bf16 v[50:65], v[140:143], v[124:127], v[50:65]
	s_waitcnt lgkmcnt(1)
	v_mfma_f32_32x32x16_bf16 v[66:81], v[144:147], v[128:131], v[66:81]
	s_waitcnt lgkmcnt(0)
	v_mfma_f32_32x32x16_bf16 v[50:65], v[148:151], v[128:131], v[50:65]
	s_cbranch_vccnz .LBB0_860
	s_setprio 0

; #define LAS __attribute__((address_space(3)))
; template <bool HAS_POST, class MaskF>
; __device__ __forceinline__ void attn_run(LAS unsigned char* lds, const bf16* Kg, const bf16* Vg, int pitch, int t0, int t1,
;                                          const bf16x8 (&qr)[4], f32x16& o0, f32x16& o1, f32x16& o2, MaskF& mf, const int wv) {
;     ...
;             LAS unsigned char* Kb = lds + (cur * 2 + j) * KBUF + cx.kroff;
;             if (wv < 4) __builtin_amdgcn_s_setprio(1);
; #pragma unroll
;             for (int d0 = 0; d0 < 4; ++d0) {
;                 const bf16x8 a0 = *(const LAS bf16x8*)(Kb + d0 * 32), a1 = *(const LAS bf16x8*)(Kb + 32 * 144 + d0 * 32);
;                 if (d0 == 0) { p0 = __builtin_amdgcn_mfma_f32_32x32x16_bf16(a0, qr[0], zc, 0, 0, 0); p1 = __builtin_amdgcn_mfma_f32_32x32x16_bf16(a1, qr[0], zc, 0, 0, 0); }
;                 else { p0 = __builtin_amdgcn_mfma_f32_32x32x16_bf16(a0, qr[d0], p0, 0, 0, 0); p1 = __builtin_amdgcn_mfma_f32_32x32x16_bf16(a1, qr[d0], p1, 0, 0, 0); }
;             }
.LBB0_867:
	s_or_b32 s0, s18, 1
	s_mul_i32 s1, s0, 0x2400
	v_add_u32_e32 v106, s1, v167
	ds_read_b128 v[102:105], v106
	ds_read_b128 v[110:113], v106 offset:32
	ds_read_b128 v[50:53], v106 offset:4608
	ds_read_b128 v[132:135], v106 offset:4640
	ds_read_b128 v[136:139], v106 offset:64
	ds_read_b128 v[140:143], v106 offset:4672
	ds_read_b128 v[144:147], v106 offset:96
	ds_read_b128 v[148:151], v106 offset:4704
	s_and_b64 vcc, exec, s[8:9]
	s_waitcnt lgkmcnt(7)
	v_mfma_f32_32x32x16_bf16 v[66:81], v[102:105], v[116:119], 0
	s_waitcnt lgkmcnt(6)
	v_mfma_f32_32x32x16_bf16 v[66:81], v[110:113], v[120:123], v[66:81]
	s_waitcnt lgkmcnt(5)
	v_mfma_f32_32x32x16_bf16 v[50:65], v[50:53], v[116:119], 0
	s_waitcnt lgkmcnt(4)
	v_mfma_f32_32x32x16_bf16 v[50:65], v[132:135], v[120:123], v[50:65]
	s_waitcnt lgkmcnt(3)
	v_mfma_f32_32x32x16_bf16 v[66:81], v[136:139], v[124:127], v[66:81]
	s_waitcnt lgkmcnt(2)
	v_mfma_f32_32x32x16_bf16 v[50:65], v[140:143], v[124:127], v[50:65]
	s_waitcnt lgkmcnt(1)
	v_mfma_f32_32x32x16_bf16 v[66:81], v[144:147], v[128:131], v[66:81]
	s_waitcnt lgkmcnt(0)
	v_mfma_f32_32x32x16_bf16 v[50:65], v[148:151], v[128:131], v[50:65]
	s_cbranch_vccnz .LBB0_869
	s_setprio 0

; #define LAS __attribute__((address_space(3)))
; template <bool HAS_POST, class MaskF>
; __device__ __forceinline__ void attn_run(LAS unsigned char* lds, const bf16* Kg, const bf16* Vg, int pitch, int t0, int t1,
;                                          const bf16x8 (&qr)[4], f32x16& o0, f32x16& o1, f32x16& o2, MaskF& mf, const int wv) {
;     ...
;             LAS unsigned char* Kb = lds + (cur * 2 + j) * KBUF + cx.kroff;
;             if (wv < 4) __builtin_amdgcn_s_setprio(1);
; #pragma unroll
;             for (int d0 = 0; d0 < 4; ++d0) {
;                 const bf16x8 a0 = *(const LAS bf16x8*)(Kb + d0 * 32), a1 = *(const LAS bf16x8*)(Kb + 32 * 144 + d0 * 32);
;                 if (d0 == 0) { p0 = __builtin_amdgcn_mfma_f32_32x32x16_bf16(a0, qr[0], zc, 0, 0, 0); p1 = __builtin_amdgcn_mfma_f32_32x32x16_bf16(a1, qr[0], zc, 0, 0, 0); }
;                 else { p0 = __builtin_amdgcn_mfma_f32_32x32x16_bf16(a0, qr[d0], p0, 0, 0, 0); p1 = __builtin_amdgcn_mfma_f32_32x32x16_bf16(a1, qr[d0], p1, 0, 0, 0); }
;             }
.LBB0_928:
	s_mul_i32 s0, s5, 0x2400
	v_add_u32_e32 v168, s0, v166
	ds_read_b128 v[50:53], v168
	ds_read_b128 v[102:105], v168 offset:32
	ds_read_b128 v[66:69], v168 offset:4608
	ds_read_b128 v[106:109], v168 offset:4640
	ds_read_b128 v[110:113], v168 offset:64
	ds_read_b128 v[132:135], v168 offset:4672
	ds_read_b128 v[136:139], v168 offset:96
	ds_read_b128 v[140:143], v168 offset:4704
	s_and_b64 vcc, exec, s[18:19]
	s_waitcnt lgkmcnt(7)
	v_mfma_f32_32x32x16_bf16 v[50:65], v[50:53], v[116:119], 0
	s_waitcnt lgkmcnt(6)
	v_mfma_f32_32x32x16_bf16 v[50:65], v[102:105], v[120:123], v[50:65]
	s_waitcnt lgkmcnt(5)
	v_mfma_f32_32x32x16_bf16 v[66:81], v[66:69], v[116:119], 0
	s_waitcnt lgkmcnt(4)
	v_mfma_f32_32x32x16_bf16 v[66:81], v[106:109], v[120:123], v[66:81]
	s_waitcnt lgkmcnt(3)
	v_mfma_f32_32x32x16_bf16 v[50:65], v[110:113], v[124:127], v[50:65]
	s_waitcnt lgkmcnt(2)
	v_mfma_f32_32x32x16_bf16 v[66:81], v[132:135], v[124:127], v[66:81]
	s_waitcnt lgkmcnt(1)
	v_mfma_f32_32x32x16_bf16 v[50:65], v[136:139], v[128:131], v[50:65]
	s_waitcnt lgkmcnt(0)
	v_mfma_f32_32x32x16_bf16 v[66:81], v[140:143], v[128:131], v[66:81]
	s_cbranch_vccnz .LBB0_930
	s_setprio 0

; #define LAS __attribute__((address_space(3)))
; template <bool HAS_POST, class MaskF>
; __device__ __forceinline__ void attn_run(LAS unsigned char* lds, const bf16* Kg, const bf16* Vg, int pitch, int t0, int t1,
;                                          const bf16x8 (&qr)[4], f32x16& o0, f32x16& o1, f32x16& o2, MaskF& mf, const int wv) {
;     ...
;             LAS unsigned char* Kb = lds + (cur * 2 + j) * KBUF + cx.kroff;
;             if (wv < 4) __builtin_amdgcn_s_setprio(1);
; #pragma unroll
;             for (int d0 = 0; d0 < 4; ++d0) {
;                 const bf16x8 a0 = *(const LAS bf16x8*)(Kb + d0 * 32), a1 = *(const LAS bf16x8*)(Kb + 32 * 144 + d0 * 32);
;                 if (d0 == 0) { p0 = __builtin_amdgcn_mfma_f32_32x32x16_bf16(a0, qr[0], zc, 0, 0, 0); p1 = __builtin_amdgcn_mfma_f32_32x32x16_bf16(a1, qr[0], zc, 0, 0, 0); }
;                 else { p0 = __builtin_amdgcn_mfma_f32_32x32x16_bf16(a0, qr[d0], p0, 0, 0, 0); p1 = __builtin_amdgcn_mfma_f32_32x32x16_bf16(a1, qr[d0], p1, 0, 0, 0); }
;             }
.LBB0_937:
	ds_read_b128 v[50:53], v168 offset:9216
	ds_read_b128 v[102:105], v168 offset:9248
	ds_read_b128 v[66:69], v168 offset:13824
	ds_read_b128 v[106:109], v168 offset:13856
	ds_read_b128 v[110:113], v168 offset:9280
	ds_read_b128 v[132:135], v168 offset:13888
	ds_read_b128 v[136:139], v168 offset:9312
	ds_read_b128 v[140:143], v168 offset:13920
	s_and_b64 vcc, exec, s[18:19]
	s_waitcnt lgkmcnt(7)
	v_mfma_f32_32x32x16_bf16 v[50:65], v[50:53], v[116:119], 0
	s_waitcnt lgkmcnt(6)
	v_mfma_f32_32x32x16_bf16 v[50:65], v[102:105], v[120:123], v[50:65]
	s_waitcnt lgkmcnt(5)
	v_mfma_f32_32x32x16_bf16 v[66:81], v[66:69], v[116:119], 0
	s_waitcnt lgkmcnt(4)
	v_mfma_f32_32x32x16_bf16 v[66:81], v[106:109], v[120:123], v[66:81]
	s_waitcnt lgkmcnt(3)
	v_mfma_f32_32x32x16_bf16 v[50:65], v[110:113], v[124:127], v[50:65]
	s_waitcnt lgkmcnt(2)
	v_mfma_f32_32x32x16_bf16 v[66:81], v[132:135], v[124:127], v[66:81]
	s_waitcnt lgkmcnt(1)
	v_mfma_f32_32x32x16_bf16 v[50:65], v[136:139], v[128:131], v[50:65]
	s_waitcnt lgkmcnt(0)
	v_mfma_f32_32x32x16_bf16 v[66:81], v[140:143], v[128:131], v[66:81]
	s_cbranch_vccnz .LBB0_939
	s_setprio 0

; #define LAS __attribute__((address_space(3)))
; template <bool HAS_POST, class MaskF>
; __device__ __forceinline__ void attn_run(LAS unsigned char* lds, const bf16* Kg, const bf16* Vg, int pitch, int t0, int t1,
;                                          const bf16x8 (&qr)[4], f32x16& o0, f32x16& o1, f32x16& o2, MaskF& mf, const int wv) {
;     ...
;             LAS unsigned char* Kb = lds + (cur * 2 + j) * KBUF + cx.kroff;
;             if (wv < 4) __builtin_amdgcn_s_setprio(1);
; #pragma unroll
;             for (int d0 = 0; d0 < 4; ++d0) {
;                 const bf16x8 a0 = *(const LAS bf16x8*)(Kb + d0 * 32), a1 = *(const LAS bf16x8*)(Kb + 32 * 144 + d0 * 32);
;                 if (d0 == 0) { p0 = __builtin_amdgcn_mfma_f32_32x32x16_bf16(a0, qr[0], zc, 0, 0, 0); p1 = __builtin_amdgcn_mfma_f32_32x32x16_bf16(a1, qr[0], zc, 0, 0, 0); }
;                 else { p0 = __builtin_amdgcn_mfma_f32_32x32x16_bf16(a0, qr[d0], p0, 0, 0, 0); p1 = __builtin_amdgcn_mfma_f32_32x32x16_bf16(a1, qr[d0], p1, 0, 0, 0); }
;             }
.LBB0_966:
	s_add_i32 s1, s96, -8
	s_and_b32 s97, s1, 2
	s_mul_i32 s1, s97, 0x2400
	v_add_u32_e32 v54, s1, v207
	ds_read_b128 v[152:155], v54
	ds_read_b128 v[156:159], v54 offset:4608
	ds_read_b128 v[160:163], v54 offset:32
	ds_read_b128 v[164:167], v54 offset:4640
	ds_read_b128 v[168:171], v54 offset:64
	ds_read_b128 v[172:175], v54 offset:4672
	ds_read_b128 v[176:179], v54 offset:96
	ds_read_b128 v[180:183], v54 offset:4704
	s_and_b64 vcc, exec, s[18:19]
	s_waitcnt lgkmcnt(7)
	v_mfma_f32_32x32x16_bf16 v[82:97], v[152:155], v[116:119], 0
	s_waitcnt lgkmcnt(6)
	v_mfma_f32_32x32x16_bf16 v[66:81], v[156:159], v[116:119], 0
	s_waitcnt lgkmcnt(5)
	v_mfma_f32_32x32x16_bf16 v[82:97], v[160:163], v[120:123], v[82:97]
	s_waitcnt lgkmcnt(4)
	v_mfma_f32_32x32x16_bf16 v[66:81], v[164:167], v[120:123], v[66:81]
	s_waitcnt lgkmcnt(3)
	v_mfma_f32_32x32x16_bf16 v[82:97], v[168:171], v[124:127], v[82:97]
	s_waitcnt lgkmcnt(2)
	v_mfma_f32_32x32x16_bf16 v[66:81], v[172:175], v[124:127], v[66:81]
	s_waitcnt lgkmcnt(1)
	v_mfma_f32_32x32x16_bf16 v[82:97], v[176:179], v[128:131], v[82:97]
	s_waitcnt lgkmcnt(0)
	v_mfma_f32_32x32x16_bf16 v[66:81], v[180:183], v[128:131], v[66:81]
	s_cbranch_vccnz .LBB0_968
	s_setprio 0

; #define LAS __attribute__((address_space(3)))
; template <bool HAS_POST, class MaskF>
; __device__ __forceinline__ void attn_run(LAS unsigned char* lds, const bf16* Kg, const bf16* Vg, int pitch, int t0, int t1,
;                                          const bf16x8 (&qr)[4], f32x16& o0, f32x16& o1, f32x16& o2, MaskF& mf, const int wv) {
;     ...
;             LAS unsigned char* Kb = lds + (cur * 2 + j) * KBUF + cx.kroff;
;             if (wv < 4) __builtin_amdgcn_s_setprio(1);
; #pragma unroll
;             for (int d0 = 0; d0 < 4; ++d0) {
;                 const bf16x8 a0 = *(const LAS bf16x8*)(Kb + d0 * 32), a1 = *(const LAS bf16x8*)(Kb + 32 * 144 + d0 * 32);
;                 if (d0 == 0) { p0 = __builtin_amdgcn_mfma_f32_32x32x16_bf16(a0, qr[0], zc, 0, 0, 0); p1 = __builtin_amdgcn_mfma_f32_32x32x16_bf16(a1, qr[0], zc, 0, 0, 0); }
;                 else { p0 = __builtin_amdgcn_mfma_f32_32x32x16_bf16(a0, qr[d0], p0, 0, 0, 0); p1 = __builtin_amdgcn_mfma_f32_32x32x16_bf16(a1, qr[d0], p1, 0, 0, 0); }
;             }
.LBB0_979:
	s_or_b32 s0, s97, 1
	s_mul_i32 s1, s0, 0x2400
	v_add_u32_e32 v86, s1, v207
	ds_read_b128 v[152:155], v86
	ds_read_b128 v[156:159], v86 offset:32
	ds_read_b128 v[50:53], v86 offset:4608
	ds_read_b128 v[160:163], v86 offset:4640
	ds_read_b128 v[164:167], v86 offset:64
	ds_read_b128 v[168:171], v86 offset:4672
	ds_read_b128 v[172:175], v86 offset:96
	ds_read_b128 v[176:179], v86 offset:4704
	s_and_b64 vcc, exec, s[18:19]
	s_waitcnt lgkmcnt(7)
	v_mfma_f32_32x32x16_bf16 v[66:81], v[152:155], v[116:119], 0
	s_waitcnt lgkmcnt(6)
	v_mfma_f32_32x32x16_bf16 v[66:81], v[156:159], v[120:123], v[66:81]
	s_waitcnt lgkmcnt(5)
	v_mfma_f32_32x32x16_bf16 v[50:65], v[50:53], v[116:119], 0
	s_waitcnt lgkmcnt(4)
	v_mfma_f32_32x32x16_bf16 v[50:65], v[160:163], v[120:123], v[50:65]
	s_waitcnt lgkmcnt(3)
	v_mfma_f32_32x32x16_bf16 v[66:81], v[164:167], v[124:127], v[66:81]
	s_waitcnt lgkmcnt(2)
	v_mfma_f32_32x32x16_bf16 v[50:65], v[168:171], v[124:127], v[50:65]
	s_waitcnt lgkmcnt(1)
	v_mfma_f32_32x32x16_bf16 v[66:81], v[172:175], v[128:131], v[66:81]
	s_waitcnt lgkmcnt(0)
	v_mfma_f32_32x32x16_bf16 v[50:65], v[176:179], v[128:131], v[50:65]
	s_cbranch_vccnz .LBB0_981
	s_setprio 0

; #define LAS __attribute__((address_space(3)))
; template <bool HAS_POST, class MaskF>
; __device__ __forceinline__ void attn_run(LAS unsigned char* lds, const bf16* Kg, const bf16* Vg, int pitch, int t0, int t1,
;                                          const bf16x8 (&qr)[4], f32x16& o0, f32x16& o1, f32x16& o2, MaskF& mf, const int wv) {
;     ...
;             LAS unsigned char* Kb = lds + (cur * 2 + j) * KBUF + cx.kroff;
;             if (wv < 4) __builtin_amdgcn_s_setprio(1);
; #pragma unroll
;             for (int d0 = 0; d0 < 4; ++d0) {
;                 const bf16x8 a0 = *(const LAS bf16x8*)(Kb + d0 * 32), a1 = *(const LAS bf16x8*)(Kb + 32 * 144 + d0 * 32);
;                 if (d0 == 0) { p0 = __builtin_amdgcn_mfma_f32_32x32x16_bf16(a0, qr[0], zc, 0, 0, 0); p1 = __builtin_amdgcn_mfma_f32_32x32x16_bf16(a1, qr[0], zc, 0, 0, 0); }
;                 else { p0 = __builtin_amdgcn_mfma_f32_32x32x16_bf16(a0, qr[d0], p0, 0, 0, 0); p1 = __builtin_amdgcn_mfma_f32_32x32x16_bf16(a1, qr[d0], p1, 0, 0, 0); }
;             }
.LBB0_1175:
	s_mul_i32 s1, s59, 0x2400
	v_add_u32_e32 v124, s1, v165
	ds_read_b128 v[120:123], v124
	ds_read_b128 v[128:131], v124 offset:32
	ds_read_b128 v[48:51], v124 offset:4608
	ds_read_b128 v[132:135], v124 offset:4640
	ds_read_b128 v[136:139], v124 offset:64
	ds_read_b128 v[140:143], v124 offset:4672
	ds_read_b128 v[144:147], v124 offset:96
	ds_read_b128 v[148:151], v124 offset:4704
	s_and_b64 vcc, exec, s[8:9]
	s_waitcnt lgkmcnt(7)
	v_mfma_f32_32x32x16_bf16 v[64:79], v[120:123], v[80:83], 0
	s_waitcnt lgkmcnt(6)
	v_mfma_f32_32x32x16_bf16 v[64:79], v[128:131], v[84:87], v[64:79]
	s_waitcnt lgkmcnt(5)
	v_mfma_f32_32x32x16_bf16 v[48:63], v[48:51], v[80:83], 0
	s_waitcnt lgkmcnt(4)
	v_mfma_f32_32x32x16_bf16 v[48:63], v[132:135], v[84:87], v[48:63]
	s_waitcnt lgkmcnt(3)
	v_mfma_f32_32x32x16_bf16 v[64:79], v[136:139], v[88:91], v[64:79]
	s_waitcnt lgkmcnt(2)
	v_mfma_f32_32x32x16_bf16 v[48:63], v[140:143], v[88:91], v[48:63]
	s_waitcnt lgkmcnt(1)
	v_mfma_f32_32x32x16_bf16 v[64:79], v[144:147], v[92:95], v[64:79]
	s_waitcnt lgkmcnt(0)
	v_mfma_f32_32x32x16_bf16 v[48:63], v[148:151], v[92:95], v[48:63]
	s_cbranch_vccnz .LBB0_1177
	s_setprio 0

; #define LAS __attribute__((address_space(3)))
; template <bool HAS_POST, class MaskF>
; __device__ __forceinline__ void attn_run(LAS unsigned char* lds, const bf16* Kg, const bf16* Vg, int pitch, int t0, int t1,
;                                          const bf16x8 (&qr)[4], f32x16& o0, f32x16& o1, f32x16& o2, MaskF& mf, const int wv) {
;     ...
;             LAS unsigned char* Kb = lds + (cur * 2 + j) * KBUF + cx.kroff;
;             if (wv < 4) __builtin_amdgcn_s_setprio(1);
; #pragma unroll
;             for (int d0 = 0; d0 < 4; ++d0) {
;                 const bf16x8 a0 = *(const LAS bf16x8*)(Kb + d0 * 32), a1 = *(const LAS bf16x8*)(Kb + 32 * 144 + d0 * 32);
;                 if (d0 == 0) { p0 = __builtin_amdgcn_mfma_f32_32x32x16_bf16(a0, qr[0], zc, 0, 0, 0); p1 = __builtin_amdgcn_mfma_f32_32x32x16_bf16(a1, qr[0], zc, 0, 0, 0); }
;                 else { p0 = __builtin_amdgcn_mfma_f32_32x32x16_bf16(a0, qr[d0], p0, 0, 0, 0); p1 = __builtin_amdgcn_mfma_f32_32x32x16_bf16(a1, qr[d0], p1, 0, 0, 0); }
;             }
.LBB0_1194:
	s_or_b32 s0, s59, 1
	s_mul_i32 s1, s0, 0x2400
	v_add_u32_e32 v124, s1, v165
	ds_read_b128 v[48:51], v124
	ds_read_b128 v[120:123], v124 offset:32
	ds_read_b128 v[64:67], v124 offset:4608
	ds_read_b128 v[128:131], v124 offset:4640
	ds_read_b128 v[132:135], v124 offset:64
	ds_read_b128 v[136:139], v124 offset:4672
	ds_read_b128 v[140:143], v124 offset:96
	ds_read_b128 v[144:147], v124 offset:4704
	s_and_b64 vcc, exec, s[10:11]
	s_waitcnt lgkmcnt(7)
	v_mfma_f32_32x32x16_bf16 v[48:63], v[48:51], v[80:83], 0
	s_waitcnt lgkmcnt(6)
	v_mfma_f32_32x32x16_bf16 v[48:63], v[120:123], v[84:87], v[48:63]
	s_waitcnt lgkmcnt(5)
	v_mfma_f32_32x32x16_bf16 v[64:79], v[64:67], v[80:83], 0
	s_waitcnt lgkmcnt(4)
	v_mfma_f32_32x32x16_bf16 v[64:79], v[128:131], v[84:87], v[64:79]
	s_waitcnt lgkmcnt(3)
	v_mfma_f32_32x32x16_bf16 v[48:63], v[132:135], v[88:91], v[48:63]
	s_waitcnt lgkmcnt(2)
	v_mfma_f32_32x32x16_bf16 v[64:79], v[136:139], v[88:91], v[64:79]
	s_waitcnt lgkmcnt(1)
	v_mfma_f32_32x32x16_bf16 v[48:63], v[140:143], v[92:95], v[48:63]
	s_waitcnt lgkmcnt(0)
	v_mfma_f32_32x32x16_bf16 v[64:79], v[144:147], v[92:95], v[64:79]
	s_cbranch_vccnz .LBB0_1196
	s_setprio 0
